# EpiProj row-scale values prefetched one unit ahead (no vmcnt(0) stall at epilogue start) + GLA prep v^T gathers batched
# speedup vs baseline: 1.1331x; 1.0009x over previous
.LBB0_109:
	s_mul_i32 s66, s90, 0x2400
	s_add_u32 s34, s12, 0x10d00000
	s_addc_u32 s35, s13, 0
	s_lshl_b64 s[36:37], s[66:67], 2
	s_sext_i32_i8 s6, s2
	s_add_u32 s2, s12, s36
	v_lshrrev_b32_e32 v16, 1, v14
	s_addc_u32 s9, s13, s37
	v_and_b32_e32 v16, 24, v16
	s_add_u32 s38, s2, 0x7000
	v_and_b32_e32 v15, 15, v14
	v_lshlrev_b32_e32 v17, 1, v16
	v_lshlrev_b32_e32 v14, 2, v14
	s_addc_u32 s39, s9, 0
	v_lshl_or_b32 v146, s8, 6, v15
	v_lshl_or_b32 v15, v15, 6, v17
	s_lshl_b32 s2, s8, 13
	v_and_b32_e32 v14, 32, v14
	v_bitop3_b32 v17, v15, s2, v14 bitop3:0xde
	s_lshl_b32 s2, s7, 5
	s_and_b32 s2, s2, 0x60
	s_add_i32 m0, s5, 0x18000
	v_lshl_add_u64 v[6:7], v[6:7], 0, s[94:95]
	s_lshl_b32 s7, s2, 7
	s_waitcnt vmcnt(2)
	s_barrier
	global_load_lds_dwordx4 v[6:7], off
	v_lshl_add_u64 v[4:5], v[4:5], 0, s[94:95]
	s_add_i32 m0, s5, 0x1a000
	s_add_i32 s66, s5, 0x8000
	s_add_i32 s84, s5, 0xa000
	global_load_lds_dwordx4 v[4:5], off
	v_lshl_add_u64 v[0:1], v[0:1], 0, s[94:95]
	s_mov_b32 m0, s66
	s_add_u32 s8, s72, 0x80080
	global_load_lds_dwordx4 v[0:1], off
	v_lshl_add_u64 v[0:1], v[2:3], 0, s[94:95]
	s_mov_b32 m0, s84
	s_addc_u32 s9, s73, 0
	global_load_lds_dwordx4 v[0:1], off
	s_add_i32 m0, s5, 0x1c000
	v_lshl_add_u64 v[0:1], s[8:9], 0, v[144:145]
	global_load_lds_dwordx4 v[0:1], off
	v_lshl_add_u64 v[0:1], s[8:9], 0, v[128:129]
	s_add_i32 m0, s5, 0x1e000
	s_cmpk_lt_u32 s3, 0x100
	global_load_lds_dwordx4 v[0:1], off
	v_lshlrev_b32_e32 v0, 15, v8
	v_and_b32_e32 v0, 0xffff0000, v0
	v_lshl_add_u32 v0, v9, 12, v0
	v_and_b32_e32 v1, 1, v8
	v_lshl_or_b32 v0, v1, 6, v0
	v_lshl_add_u32 v134, v10, 1, v0
	v_lshlrev_b32_e32 v0, 15, v12
	v_and_b32_e32 v0, 0xffff0000, v0
	s_waitcnt vmcnt(6)
	v_lshl_add_u32 v0, v11, 12, v0
	v_and_b32_e32 v1, 1, v12
	v_lshl_or_b32 v0, v1, 6, v0
	v_bitop3_b32 v162, v15, s7, v14 bitop3:0xde
	s_cselect_b64 s[40:41], -1, 0
	v_or_b32_e32 v163, s2, v16
	v_mov_b32_e32 v135, v145
	v_lshl_add_u32 v136, v13, 1, v0
	v_mov_b32_e32 v137, v145
	s_mov_b32 s88, 0
	v_add_u32_e32 v164, 0, v17
	s_barrier
	v_lshl_add_u32 v247, s4, 8, v146
	v_lshlrev_b32_e32 v247, 2, v247
	global_load_dword v248, v247, s[38:39]
	global_load_dword v249, v247, s[38:39] offset:64
	global_load_dword v250, v247, s[38:39] offset:128
	global_load_dword v251, v247, s[38:39] offset:192
	global_load_dword v252, v247, s[38:39] offset:512
	global_load_dword v253, v247, s[38:39] offset:576
	global_load_dword v254, v247, s[38:39] offset:640
	global_load_dword v255, v247, s[38:39] offset:704
	s_mov_b32 s100, 15
	s_branch .LBB0_112

.LBB0_118:
	v_lshl_add_u32 v142, s4, 8, v146
	v_lshl_or_b32 v138, s6, 8, v163
	v_ashrrev_i32_e32 v143, 31, v142
	v_ashrrev_i32_e32 v139, 31, v138
	v_lshlrev_b64 v[140:141], 13, v[142:143]
	v_lshl_add_u64 v[140:141], s[34:35], 0, v[140:141]
	v_lshlrev_b64 v[160:161], 1, v[138:139]
	v_lshl_add_u64 v[138:139], v[140:141], 0, v[160:161]
	v_lshl_add_u64 v[140:141], v[142:143], 2, s[38:39]
	v_mov_b32_e32 v200, v248
	v_mov_b32_e32 v201, v249
	v_mov_b32_e32 v202, v250
	v_mov_b32_e32 v203, v251
	v_mov_b32_e32 v204, v252
	v_mov_b32_e32 v205, v253
	v_mov_b32_e32 v206, v254
	v_mov_b32_e32 v207, v255
	s_min_u32 s32, s54, 35
	v_lshl_add_u32 v247, s32, 8, v146
	v_lshlrev_b32_e32 v247, 2, v247
	global_load_dword v248, v247, s[38:39]
	global_load_dword v249, v247, s[38:39] offset:64
	global_load_dword v250, v247, s[38:39] offset:128
	global_load_dword v251, v247, s[38:39] offset:192
	global_load_dword v252, v247, s[38:39] offset:512
	global_load_dword v253, v247, s[38:39] offset:576
	global_load_dword v254, v247, s[38:39] offset:640
	global_load_dword v255, v247, s[38:39] offset:704
	v_mov_b32_e32 v143, v200
	s_mov_b32 s2, 0x100000
	s_mov_b32 s89, 0x18000
	v_fmamk_f32 v143, v143, 0x3a000000, v181
	v_cmp_gt_f32_e32 vcc, s80, v143
	v_mul_f32_e32 v165, 0x4b800000, v143
	s_nop 0
	v_cndmask_b32_e32 v143, v143, v165, vcc
	v_rsq_f32_e32 v143, v143
	s_nop 0
	v_mul_f32_e32 v165, 0x45800000, v143
	v_cndmask_b32_e32 v166, v143, v165, vcc
	v_pk_mul_f32 v[126:127], v[126:127], v[166:167] op_sel_hi:[1,0]
	v_pk_mul_f32 v[124:125], v[124:125], v[166:167] op_sel_hi:[1,0]
	v_pk_mul_f32 v[168:169], v[122:123], v[166:167] op_sel_hi:[1,0]
	v_pk_mul_f32 v[122:123], v[120:121], v[166:167] op_sel_hi:[1,0]
	v_cvt_pk_bf16_f32 v120, v124, v125
	v_cvt_pk_bf16_f32 v121, v126, v127
	v_pk_mul_f32 v[116:117], v[116:117], v[166:167] op_sel_hi:[1,0]
	v_cvt_pk_bf16_f32 v122, v122, v123
	v_cvt_pk_bf16_f32 v123, v168, v169
	s_bitcmp1_b32 s100, 0
	s_cbranch_scc0 .Lq_lin_e0
	flat_store_dwordx4 v[138:139], v[120:123]

.LBB0_620:
	s_mul_i32 s14, s90, 0x2400
	s_mov_b32 s15, s67
	s_add_u32 s30, s12, 0x10d00000
	s_addc_u32 s31, s13, 0
	s_lshl_b64 s[40:41], s[14:15], 2
	s_mov_b32 s24, s14
	s_add_u32 s14, s12, s40
	s_addc_u32 s15, s13, s41
	s_add_u32 s40, s14, 0x7000
	s_addc_u32 s41, s15, 0
	s_lshl_b32 s15, s36, 5
	s_and_b32 s15, s15, 0x60
	s_add_i32 m0, s5, 0x18000
	v_lshl_add_u64 v[6:7], v[6:7], 0, s[94:95]
	s_lshl_b32 s14, s9, 13
	s_lshl_b32 s39, s15, 7
	s_waitcnt vmcnt(2)
	s_barrier
	global_load_lds_dwordx4 v[6:7], off
	v_lshl_add_u64 v[4:5], v[4:5], 0, s[94:95]
	s_add_i32 m0, s5, 0x1a000
	s_add_i32 s61, s5, 0x8000
	s_add_i32 s62, s5, 0xa000
	global_load_lds_dwordx4 v[4:5], off
	v_lshl_add_u64 v[0:1], v[0:1], 0, s[94:95]
	s_mov_b32 m0, s61
	s_add_u32 s36, s2, 0x80080
	global_load_lds_dwordx4 v[0:1], off
	v_lshl_add_u64 v[0:1], v[2:3], 0, s[94:95]
	s_mov_b32 m0, s62
	s_addc_u32 s37, s3, 0
	global_load_lds_dwordx4 v[0:1], off
	s_add_i32 m0, s5, 0x1c000
	v_lshl_add_u64 v[0:1], s[36:37], 0, v[144:145]
	global_load_lds_dwordx4 v[0:1], off
	v_lshl_add_u64 v[0:1], s[36:37], 0, v[132:133]
	s_add_i32 m0, s5, 0x1e000
	v_writelane_b32 v244, s24, 17
	global_load_lds_dwordx4 v[0:1], off
	v_lshrrev_b32_e32 v1, 1, v8
	v_and_b32_e32 v1, 24, v1
	v_and_b32_e32 v0, 15, v8
	v_lshlrev_b32_e32 v2, 1, v1
	v_lshl_or_b32 v143, s9, 6, v0
	v_lshl_or_b32 v0, v0, 6, v2
	v_lshlrev_b32_e32 v2, 2, v8
	v_and_b32_e32 v2, 32, v2
	v_bitop3_b32 v3, v0, s14, v2 bitop3:0xde
	v_bitop3_b32 v160, v0, s39, v2 bitop3:0xde
	v_lshlrev_b32_e32 v0, 15, v12
	v_and_b32_e32 v0, 0xffff0000, v0
	v_or_b32_e32 v161, s15, v1
	v_lshl_add_u32 v0, v13, 12, v0
	v_and_b32_e32 v1, 1, v12
	v_lshl_or_b32 v0, v1, 6, v0
	v_writelane_b32 v244, s25, 18
	s_cmpk_lt_u32 s8, 0x100
	v_lshl_add_u32 v134, v14, 1, v0
	v_lshlrev_b32_e32 v0, 15, v9
	s_cselect_b64 s[52:53], -1, 0
	s_ashr_i32 s63, s6, 31
	v_readlane_b32 s24, v244, 13
	v_and_b32_e32 v0, 0xffff0000, v0
	s_waitcnt vmcnt(6)
	s_cmp_lg_u64 s[40:41], 0
	v_readlane_b32 s25, v244, 14
	v_lshl_add_u32 v0, v10, 12, v0
	v_and_b32_e32 v1, 1, v9
	s_cselect_b64 s[8:9], -1, 0
	s_xor_b64 s[36:37], s[24:25], -1
	v_lshl_or_b32 v0, v1, 6, v0
	s_and_b64 s[54:55], s[36:37], s[8:9]
	v_mov_b32_e32 v135, v145
	v_lshl_add_u32 v136, v11, 1, v0
	v_mov_b32_e32 v137, v145
	s_mov_b32 s64, 0
	v_add_u32_e32 v162, 0, v3
	s_barrier
	s_cmp_eq_u64 s[54:55], 0
	s_cbranch_scc1 .Lssp_abi_skip
	v_lshl_add_u32 v247, s38, 8, v143
	v_lshlrev_b32_e32 v247, 2, v247
	global_load_dword v248, v247, s[40:41]
	global_load_dword v249, v247, s[40:41] offset:64
	global_load_dword v250, v247, s[40:41] offset:128
	global_load_dword v251, v247, s[40:41] offset:192
	global_load_dword v252, v247, s[40:41] offset:512
	global_load_dword v253, v247, s[40:41] offset:576
	global_load_dword v254, v247, s[40:41] offset:640
	global_load_dword v255, v247, s[40:41] offset:704
.Lssp_abi_skip:
	s_mov_b32 s100, 15
	s_branch .LBB0_623

.LBB0_633:
	v_lshl_add_u32 v138, s38, 8, v143
	v_cndmask_b32_e64 v140, 0, 1, s[54:55]
	v_ashrrev_i32_e32 v139, 31, v138
	v_mov_b32_e32 v142, 1.0
	v_cmp_ne_u32_e64 s[38:39], 1, v140
	s_andn2_b64 vcc, exec, s[54:55]
	v_mov_b32_e32 v146, 1.0
	s_cbranch_vccnz .LBB0_635
	v_lshl_add_u64 v[140:141], v[138:139], 2, s[40:41]
	v_mov_b32_e32 v200, v248
	v_mov_b32_e32 v201, v249
	v_mov_b32_e32 v202, v250
	v_mov_b32_e32 v203, v251
	v_mov_b32_e32 v204, v252
	v_mov_b32_e32 v205, v253
	v_mov_b32_e32 v206, v254
	v_mov_b32_e32 v207, v255
	s_min_u32 s32, s82, 35
	v_lshl_add_u32 v247, s32, 8, v143
	v_lshlrev_b32_e32 v247, 2, v247
	global_load_dword v248, v247, s[40:41]
	global_load_dword v249, v247, s[40:41] offset:64
	global_load_dword v250, v247, s[40:41] offset:128
	global_load_dword v251, v247, s[40:41] offset:192
	global_load_dword v252, v247, s[40:41] offset:512
	global_load_dword v253, v247, s[40:41] offset:576
	global_load_dword v254, v247, s[40:41] offset:640
	global_load_dword v255, v247, s[40:41] offset:704
	v_mov_b32_e32 v139, v200
	v_fmamk_f32 v139, v139, 0x3a000000, v181
	v_mul_f32_e32 v140, 0x4b800000, v139
	v_cmp_gt_f32_e32 vcc, s80, v139
	s_nop 1
	v_cndmask_b32_e32 v139, v139, v140, vcc
	v_rsq_f32_e32 v139, v139
	s_nop 0
	v_mul_f32_e32 v140, 0x45800000, v139
	v_cndmask_b32_e32 v146, v139, v140, vcc

.LBB0_767:
	v_add_u32_e32 v226, 0, v6
	v_ashrrev_i32_e32 v227, 5, v226
	v_and_b32_e32 v227, -8, v227
	v_add_u32_e32 v227, s6, v227
	v_mul_lo_u32 v222, v227, s86
	v_add3_u32 v222, v222, s66, v144
	v_add_u32_e32 v224, 0x2820, v222
	global_load_ushort v190, v224, s[28:29]
	v_add_u32_e32 v224, 0x6220, v222
	global_load_ushort v191, v224, s[28:29]
	v_add_u32_e32 v224, 0x9c20, v222
	global_load_ushort v192, v224, s[28:29]
	v_add_u32_e32 v224, 0xd620, v222
	global_load_ushort v193, v224, s[28:29]
	v_add_u32_e32 v224, 0x11020, v222
	global_load_ushort v194, v224, s[28:29]
	v_add_u32_e32 v224, 0x14a20, v222
	global_load_ushort v195, v224, s[28:29]
	v_add_u32_e32 v224, 0x18420, v222
	global_load_ushort v196, v224, s[28:29]
	v_add_u32_e32 v224, 0x1be20, v222
	global_load_ushort v197, v224, s[28:29]
	v_add_u32_e32 v226, 512, v6
	v_ashrrev_i32_e32 v227, 5, v226
	v_and_b32_e32 v227, -8, v227
	v_add_u32_e32 v227, s6, v227
	v_mul_lo_u32 v222, v227, s86
	v_add3_u32 v222, v222, s66, v144
	v_add_u32_e32 v224, 0x2820, v222
	global_load_ushort v198, v224, s[28:29]
	v_add_u32_e32 v224, 0x6220, v222
	global_load_ushort v199, v224, s[28:29]
	v_add_u32_e32 v224, 0x9c20, v222
	global_load_ushort v200, v224, s[28:29]
	v_add_u32_e32 v224, 0xd620, v222
	global_load_ushort v201, v224, s[28:29]
	v_add_u32_e32 v224, 0x11020, v222
	global_load_ushort v202, v224, s[28:29]
	v_add_u32_e32 v224, 0x14a20, v222
	global_load_ushort v203, v224, s[28:29]
	v_add_u32_e32 v224, 0x18420, v222
	global_load_ushort v204, v224, s[28:29]
	v_add_u32_e32 v224, 0x1be20, v222
	global_load_ushort v205, v224, s[28:29]
	v_add_u32_e32 v226, 1024, v6
	v_ashrrev_i32_e32 v227, 5, v226
	v_and_b32_e32 v227, -8, v227
	v_add_u32_e32 v227, s6, v227
	v_mul_lo_u32 v222, v227, s86
	v_add3_u32 v222, v222, s66, v144
	v_add_u32_e32 v224, 0x2820, v222
	global_load_ushort v206, v224, s[28:29]
	v_add_u32_e32 v224, 0x6220, v222
	global_load_ushort v207, v224, s[28:29]
	v_add_u32_e32 v224, 0x9c20, v222
	global_load_ushort v208, v224, s[28:29]
	v_add_u32_e32 v224, 0xd620, v222
	global_load_ushort v209, v224, s[28:29]
	v_add_u32_e32 v224, 0x11020, v222
	global_load_ushort v210, v224, s[28:29]
	v_add_u32_e32 v224, 0x14a20, v222
	global_load_ushort v211, v224, s[28:29]
	v_add_u32_e32 v224, 0x18420, v222
	global_load_ushort v212, v224, s[28:29]
	v_add_u32_e32 v224, 0x1be20, v222
	global_load_ushort v213, v224, s[28:29]
	v_add_u32_e32 v226, 1536, v6
	v_ashrrev_i32_e32 v227, 5, v226
	v_and_b32_e32 v227, -8, v227
	v_add_u32_e32 v227, s6, v227
	v_mul_lo_u32 v222, v227, s86
	v_add3_u32 v222, v222, s66, v144
	v_add_u32_e32 v224, 0x2820, v222
	global_load_ushort v214, v224, s[28:29]
	v_add_u32_e32 v224, 0x6220, v222
	global_load_ushort v215, v224, s[28:29]
	v_add_u32_e32 v224, 0x9c20, v222
	global_load_ushort v216, v224, s[28:29]
	v_add_u32_e32 v224, 0xd620, v222
	global_load_ushort v217, v224, s[28:29]
	v_add_u32_e32 v224, 0x11020, v222
	global_load_ushort v218, v224, s[28:29]
	v_add_u32_e32 v224, 0x14a20, v222
	global_load_ushort v219, v224, s[28:29]
	v_add_u32_e32 v224, 0x18420, v222
	global_load_ushort v220, v224, s[28:29]
	v_add_u32_e32 v224, 0x1be20, v222
	global_load_ushort v221, v224, s[28:29]
	s_waitcnt vmcnt(24)
	v_lshl_or_b32 v190, v190, 16, v185
	v_lshl_or_b32 v191, v191, 16, v185
	v_perm_b32 v228, v191, v190, s81
	v_lshl_or_b32 v192, v192, 16, v185
	v_lshl_or_b32 v193, v193, 16, v185
	v_perm_b32 v229, v193, v192, s81
	v_lshl_or_b32 v194, v194, 16, v185
	v_lshl_or_b32 v195, v195, 16, v185
	v_perm_b32 v230, v195, v194, s81
	v_lshl_or_b32 v196, v196, 16, v185
	v_lshl_or_b32 v197, v197, 16, v185
	v_perm_b32 v231, v197, v196, s81
	s_waitcnt vmcnt(16)
	v_lshl_or_b32 v198, v198, 16, v185
	v_lshl_or_b32 v199, v199, 16, v185
	v_perm_b32 v232, v199, v198, s81
	v_lshl_or_b32 v200, v200, 16, v185
	v_lshl_or_b32 v201, v201, 16, v185
	v_perm_b32 v233, v201, v200, s81
	v_lshl_or_b32 v202, v202, 16, v185
	v_lshl_or_b32 v203, v203, 16, v185
	v_perm_b32 v234, v203, v202, s81
	v_lshl_or_b32 v204, v204, 16, v185
	v_lshl_or_b32 v205, v205, 16, v185
	v_perm_b32 v235, v205, v204, s81
	s_waitcnt vmcnt(8)
	v_lshl_or_b32 v206, v206, 16, v185
	v_lshl_or_b32 v207, v207, 16, v185
	v_perm_b32 v236, v207, v206, s81
	v_lshl_or_b32 v208, v208, 16, v185
	v_lshl_or_b32 v209, v209, 16, v185
	v_perm_b32 v237, v209, v208, s81
	v_lshl_or_b32 v210, v210, 16, v185
	v_lshl_or_b32 v211, v211, 16, v185
	v_perm_b32 v238, v211, v210, s81
	v_lshl_or_b32 v212, v212, 16, v185
	v_lshl_or_b32 v213, v213, 16, v185
	v_perm_b32 v239, v213, v212, s81
	s_waitcnt vmcnt(0)
	v_lshl_or_b32 v214, v214, 16, v185
	v_lshl_or_b32 v215, v215, 16, v185
	v_perm_b32 v240, v215, v214, s81
	v_lshl_or_b32 v216, v216, 16, v185
	v_lshl_or_b32 v217, v217, 16, v185
	v_perm_b32 v241, v217, v216, s81
	v_lshl_or_b32 v218, v218, 16, v185
	v_lshl_or_b32 v219, v219, 16, v185
	v_perm_b32 v242, v219, v218, s81
	v_lshl_or_b32 v220, v220, 16, v185
	v_lshl_or_b32 v221, v221, 16, v185
	v_perm_b32 v243, v221, v220, s81
	v_add_u32_e32 v226, 0, v6
	v_ashrrev_i32_e32 v227, 5, v226
	v_lshlrev_b32_e32 v227, 1, v227
	v_and_b32_e32 v227, 48, v227
	v_ashrrev_i32_e32 v224, 10, v226
	v_lshrrev_b32_e32 v222, 3, v226
	v_and_b32_e32 v222, 30, v222
	v_add_lshl_u32 v222, v222, v224, 6
	v_or3_b32 v222, v222, v227, v13
	v_lshlrev_b32_e32 v222, 4, v222
	global_store_dwordx4 v222, v[228:231], s[8:9]
	v_add_u32_e32 v226, 512, v6
	v_ashrrev_i32_e32 v227, 5, v226
	v_lshlrev_b32_e32 v227, 1, v227
	v_and_b32_e32 v227, 48, v227
	v_ashrrev_i32_e32 v224, 10, v226
	v_lshrrev_b32_e32 v222, 3, v226
	v_and_b32_e32 v222, 30, v222
	v_add_lshl_u32 v222, v222, v224, 6
	v_or3_b32 v222, v222, v227, v13
	v_lshlrev_b32_e32 v222, 4, v222
	global_store_dwordx4 v222, v[232:235], s[8:9]
	v_add_u32_e32 v226, 1024, v6
	v_ashrrev_i32_e32 v227, 5, v226
	v_lshlrev_b32_e32 v227, 1, v227
	v_and_b32_e32 v227, 48, v227
	v_ashrrev_i32_e32 v224, 10, v226
	v_lshrrev_b32_e32 v222, 3, v226
	v_and_b32_e32 v222, 30, v222
	v_add_lshl_u32 v222, v222, v224, 6
	v_or3_b32 v222, v222, v227, v13
	v_lshlrev_b32_e32 v222, 4, v222
	global_store_dwordx4 v222, v[236:239], s[8:9]
	v_add_u32_e32 v226, 1536, v6
	v_ashrrev_i32_e32 v227, 5, v226
	v_lshlrev_b32_e32 v227, 1, v227
	v_and_b32_e32 v227, 48, v227
	v_ashrrev_i32_e32 v224, 10, v226
	v_lshrrev_b32_e32 v222, 3, v226
	v_and_b32_e32 v222, 30, v222
	v_add_lshl_u32 v222, v222, v224, 6
	v_or3_b32 v222, v222, v227, v13
	v_lshlrev_b32_e32 v222, 4, v222
	global_store_dwordx4 v222, v[240:243], s[8:9]
	s_mov_b64 s[12:13], exec
